# attention K tile LDS XOR swizzle (chunk ^= ((key>>2)^(key>>3))&1) for conflict-free ds_read_b128
# baseline (speedup 1.0000x reference)
; __device__ __forceinline__ void attn_phase(const Params& p, char* smem) {
;   const int tid = otid(), lane = tid & 63, w = tid >> 6, fr = lane & 15, fq = lane >> 4;
;   bf16_t* Ks = (bf16_t*)smem;
;   bf16_t* Vt = Ks + 2 * KT * KLD;
;   const bf16_t* Qg = p.ACT();
;   const bf16_t* Kg = p.ACT() + (size_t)16 * TPB * 96;
;   const bf16_t* KVRAW = p.R() + (size_t)NTOK * 768;
;   bf16_t* MIX = p.H();
;   for (int it = obid(); it < 272; it += gridDim.x) {
;     int bh, qu0, nq, nkeys;
;     if (it < 256) { int xx = it & 7, k = it >> 3; bh = 2 * xx + (k >> 4); qu0 = CTX + (k & 15) * 512; nq = 512; nkeys = TPB; }
;     else { bh = it - 256; qu0 = 0; nq = 256; nkeys = CTX; }
;     const int b = bh >> 3, h = bh & 7;
;     const bool active = (w * 64) < nq;
;     bf16x8 qf[4][3];
;     if (active) {
; #pragma unroll
;       for (int g = 0; g < 4; ++g) {
;         const bf16_t* qp = Qg + ((size_t)bh * TPB + qu0 + w * 64 + g * 16 + fr) * 96 + fq * 8;
; #pragma unroll
;         for (int ds = 0; ds < 3; ++ds) qf[g][ds] = *(const bf16x8*)(qp + ds * 32);
;       }
;     }
;     f32x4 oT[4][4];
;     float mneg[4], lrun[4];
;     float bmax = 0.f;
;     {
;       const float kmx = sqrtf(__uint_as_float(p.kmax2()[bh]) + __uint_as_float(p.kmax2()[16 + bh])) * 1.01f;
; #pragma unroll
;       for (int g = 0; g < 4; ++g) {
;         float qs = 0.f;
;         if (active) {
; #pragma unroll
;           for (int ds = 0; ds < 3; ++ds)
; #pragma unroll
;             for (int e = 0; e < 8; ++e) { float qv = bf2f((bf16_t)qf[g][ds][e]); qs += qv * qv; }
;         }
;         qs += __shfl_xor(qs, 16); qs += __shfl_xor(qs, 32);
;         mneg[g] = -sqrtf(qs) * kmx;
;         bmax = fmaxf(bmax, -mneg[g]);
;         lrun[g] = 0.f;
; #pragma unroll
;         for (int q = 0; q < 4; ++q) oT[g][q] = (f32x4){0.f, 0.f, 0.f, 0.f};
;       }
;     }
;     const bool stab = __any(bmax > 60.0f) != 0;
;     const bf16_t* kbase = Kg + (size_t)bh * TPB * 96;
;     const bf16_t* vbase = KVRAW + (size_t)b * TPB * 1024 + h * 128 + 64;
;     ...
;     uint4 rk0, rk1, rk2, rv0, rv1;
;     const int nkt = nkeys / KT;
;     rk0 = *(const uint4*)(kbase + kgo); rk1 = *(const uint4*)(kbase + kgo + 8); rk2 = *(const uint4*)(kbase + kgo + 16);
;     rv0 = *(const uint4*)(vbase + (size_t)vkey0 * 1024 + vch * 8); rv1 = *(const uint4*)(vbase + (size_t)(vkey0 + 64) * 1024 + vch * 8);
.LBB0_392:
	s_and_b64 vcc, exec, s[2:3]
	s_cbranch_vccz .LBB0_426
	v_mov_b32_e32 v0, v164
	s_mov_b32 s12, s82
	s_cmpk_gt_i32 s12, 0x10f
	s_cbranch_scc1 .LBB0_426
	s_load_dwordx2 s[44:45], s[0:1], 0xf0
	v_bfe_u32 v1, v0, 4, 2
	v_lshlrev_b32_e32 v2, 4, v1
	v_mov_b32_e32 v3, v167
	v_lshlrev_b32_e32 v166, 3, v1
	s_waitcnt lgkmcnt(0)
	v_lshl_add_u64 v[4:5], s[44:45], 0, v[2:3]
	v_and_b32_e32 v3, 64, v231
	v_xor_b32_e32 v1, 16, v231
	v_add_u32_e32 v3, 64, v3
	v_cmp_lt_i32_e32 vcc, v1, v3
	s_mov_b64 s[2:3], 0x7290000
	v_lshl_add_u64 v[180:181], v[4:5], 0, s[2:3]
	v_cndmask_b32_e32 v1, v231, v1, vcc
	v_lshlrev_b32_e32 v235, 2, v1
	v_xor_b32_e32 v1, 32, v231
	v_cmp_lt_i32_e32 vcc, v1, v3
	s_movk_i32 s2, 0x60
	v_and_b32_e32 v4, 3, v0
	v_cndmask_b32_e32 v1, v231, v1, vcc
	v_lshlrev_b32_e32 v236, 2, v1
	v_ashrrev_i32_e32 v1, 2, v0
	v_mul_lo_u32 v3, v1, s2
	v_mul_u32_u24_e32 v10, 24, v4
	v_mad_u32_u24 v4, v4, 24, v3
	v_and_b32_e32 v6, 63, v0
	v_lshrrev_b32_e32 v3, 3, v0
	s_movk_i32 s4, 0xd0
	v_ashrrev_i32_e32 v7, 31, v6
	v_and_b32_e32 v8, 56, v3
	v_mul_lo_u32 v1, v1, s4
	v_lshlrev_b32_e32 v3, 1, v10
	v_lshlrev_b64 v[182:183], 11, v[6:7]
	s_mov_b64 s[2:3], 0x20000
	v_add3_u32 v237, 0, v1, v3
	v_mul_u32_u24_e32 v1, 0x110, v8
	v_lshlrev_b32_e32 v3, 1, v6
	v_and_b32_e32 v9, 15, v0
	v_and_b32_e32 v171, 0xffffffc0, v0
	v_ashrrev_i32_e32 v5, 31, v4
	v_lshl_add_u64 v[184:185], v[182:183], 0, s[2:3]
	v_add3_u32 v238, 0, v1, v3
	v_and_b32_e32 v239, 0xffffffcf, v0
	v_lshl_add_u64 v[0:1], s[44:45], 0, v[166:167]
	s_mov_b64 s[2:3], 0x5190000
	v_lshl_add_u64 v[186:187], v[0:1], 0, s[2:3]
	v_lshl_add_u64 v[0:1], v[4:5], 1, s[44:45]
	s_mov_b64 s[2:3], 0x8b50000
	v_lshl_add_u64 v[188:189], v[0:1], 0, s[2:3]
	s_add_u32 s13, s44, 0x115d0900
	s_movk_i32 s2, 0x110
	v_ashrrev_i32_e32 v179, 31, v171
	v_or_b32_e32 v178, v171, v9
	s_addc_u32 s14, s45, 0
	v_mad_u32_u24 v240, v9, s2, v166
	v_lshrrev_b32_e32 v0, 2, v9
	v_lshrrev_b32_e32 v1, 3, v9
	v_xor_b32_e32 v0, v0, v1
	v_and_b32_e32 v0, 1, v0
	v_lshlrev_b32_e32 v0, 4, v0
	v_xor_b32_e32 v0, v2, v0
	v_mad_u32_u24 v241, v9, s4, v0
	v_lshlrev_b32_e32 v166, 1, v8
	s_branch .LBB0_396

;   __host__ __device__ __forceinline__ unsigned* kmax2() const { return (unsigned*)(wsl() + OFF_KMAX); }
; __device__ __forceinline__ float bf2f(bf16_t h) { return __uint_as_float(((uint32_t)h) << 16); }
; __device__ __forceinline__ void attn_phase(const Params& p, char* smem) {
;     ...
;     float mneg[4], lrun[4];
;     float bmax = 0.f;
;     {
;       const float kmx = sqrtf(__uint_as_float(p.kmax2()[bh]) + __uint_as_float(p.kmax2()[16 + bh])) * 1.01f;
; #pragma unroll
;       for (int g = 0; g < 4; ++g) {
;         float qs = 0.f;
;         if (active) {
; #pragma unroll
;           for (int ds = 0; ds < 3; ++ds)
; #pragma unroll
;             for (int e = 0; e < 8; ++e) { float qv = bf2f((bf16_t)qf[g][ds][e]); qs += qv * qv; }
;         }
;         qs += __shfl_xor(qs, 16); qs += __shfl_xor(qs, 32);
;         mneg[g] = -sqrtf(qs) * kmx;
;         bmax = fmaxf(bmax, -mneg[g]);
;         lrun[g] = 0.f;
; #pragma unroll
;         for (int q = 0; q < 4; ++q) oT[g][q] = (f32x4){0.f, 0.f, 0.f, 0.f};
;       }
;     }
;     const bool stab = __any(bmax > 60.0f) != 0;
;     const bf16_t* kbase = Kg + (size_t)bh * TPB * 96;
;     const bf16_t* vbase = KVRAW + (size_t)b * TPB * 1024 + h * 128 + 64;
;     ...
;     uint4 rk0, rk1, rk2, rv0, rv1;
;     const int nkt = nkeys / KT;
;     rk0 = *(const uint4*)(kbase + kgo); rk1 = *(const uint4*)(kbase + kgo + 8); rk2 = *(const uint4*)(kbase + kgo + 16);
;     rv0 = *(const uint4*)(vbase + (size_t)vkey0 * 1024 + vch * 8); rv1 = *(const uint4*)(vbase + (size_t)(vkey0 + 64) * 1024 + vch * 8);
;     {
;       *(uint4*)(Ks + klo) = rk0; *(uint4*)(Ks + klo + 8) = rk1; *(uint4*)(Ks + klo + 16) = rk2;
;       vt_scatter(Vt + (vch * 8) * VLD + vkey0, VLD, rv0); vt_scatter(Vt + (vch * 8) * VLD + vkey0 + 64, VLD, rv1);
;     }
;     __syncthreads();
.LBB0_410:
	s_or_b64 exec, exec, s[4:5]
	s_waitcnt vmcnt(0)
	v_add_f32_e32 v48, v48, v49
	s_mov_b32 s3, 0xf800000
	v_mul_f32_e32 v49, 0x4f800000, v48
	v_cmp_gt_f32_e32 vcc, s3, v48
	v_add_f32_e32 v50, v50, v51
	v_mul_f32_e32 v51, 0x4f800000, v50
	v_cndmask_b32_e32 v48, v48, v49, vcc
	v_sqrt_f32_e32 v49, v48
	s_mov_b32 s4, 0x42700000
	s_ashr_i32 s15, s6, 3
	s_mul_i32 s8, s15, 0x1080000
	v_add_u32_e32 v57, -1, v49
	v_fma_f32 v59, -v57, v49, v48
	v_add_u32_e32 v58, 1, v49
	v_cmp_ge_f32_e64 s[42:43], 0, v59
	s_mul_hi_i32 s7, s15, 0x1080000
	v_mov_b32_e32 v80, v167
	v_cndmask_b32_e64 v57, v49, v57, s[42:43]
	v_fma_f32 v49, -v58, v49, v48
	v_cmp_lt_f32_e64 s[42:43], 0, v49
	v_mov_b32_e32 v81, v167
	v_mov_b32_e32 v82, v167
	v_cndmask_b32_e64 v49, v57, v58, s[42:43]
	v_mul_f32_e32 v57, 0x37800000, v49
	v_cndmask_b32_e32 v49, v49, v57, vcc
	v_cmp_gt_f32_e32 vcc, s3, v50
	v_cmp_class_f32_e64 s[42:43], v48, v216
	v_mov_b32_e32 v83, v167
	v_cndmask_b32_e32 v50, v50, v51, vcc
	v_sqrt_f32_e32 v51, v50
	v_cndmask_b32_e64 v48, v49, v48, s[42:43]
	v_mul_f32_e32 v48, 0x3f8147ae, v48
	v_mov_b32_e32 v190, v167
	v_add_u32_e32 v49, -1, v51
	v_fma_f32 v57, -v49, v51, v50
	v_cmp_ge_f32_e64 s[42:43], 0, v57
	v_add_u32_e32 v57, 1, v51
	v_mov_b32_e32 v191, v167
	v_cndmask_b32_e64 v49, v51, v49, s[42:43]
	v_fma_f32 v51, -v57, v51, v50
	v_cmp_lt_f32_e64 s[42:43], 0, v51
	v_mov_b64_e32 v[86:87], v[82:83]
	v_mov_b64_e32 v[90:91], v[82:83]
	v_cndmask_b32_e64 v49, v49, v57, s[42:43]
	v_mul_f32_e32 v51, 0x37800000, v49
	v_cndmask_b32_e32 v49, v49, v51, vcc
	v_add_f32_e32 v51, v52, v53
	v_mul_f32_e32 v52, 0x4f800000, v51
	v_cmp_gt_f32_e32 vcc, s3, v51
	v_cmp_class_f32_e64 s[42:43], v50, v216
	v_mov_b64_e32 v[94:95], v[82:83]
	v_cndmask_b32_e32 v51, v51, v52, vcc
	v_sqrt_f32_e32 v52, v51
	v_cndmask_b32_e64 v49, v49, v50, s[42:43]
	v_mul_f32_e64 v192, v48, -v49
	v_mov_b64_e32 v[98:99], v[82:83]
	v_add_u32_e32 v49, -1, v52
	v_fma_f32 v50, -v49, v52, v51
	v_cmp_ge_f32_e64 s[42:43], 0, v50
	v_add_u32_e32 v50, 1, v52
	v_mov_b64_e32 v[102:103], v[82:83]
	v_cndmask_b32_e64 v49, v52, v49, s[42:43]
	v_fma_f32 v52, -v50, v52, v51
	v_cmp_lt_f32_e64 s[42:43], 0, v52
	v_mov_b64_e32 v[106:107], v[82:83]
	v_mov_b64_e32 v[110:111], v[82:83]
	v_cndmask_b32_e64 v49, v49, v50, s[42:43]
	v_mul_f32_e32 v50, 0x37800000, v49
	v_cndmask_b32_e32 v49, v49, v50, vcc
	s_waitcnt lgkmcnt(0)
	v_add_f32_e32 v50, v55, v56
	v_mul_f32_e32 v52, 0x4f800000, v50
	v_cmp_gt_f32_e32 vcc, s3, v50
	v_cmp_class_f32_e64 s[42:43], v51, v216
	v_mov_b64_e32 v[76:77], v[80:81]
	v_cndmask_b32_e32 v50, v50, v52, vcc
	v_sqrt_f32_e32 v52, v50
	v_cndmask_b32_e64 v49, v49, v51, s[42:43]
	v_mul_f32_e64 v196, v48, -v49
	v_max3_f32 v49, -v192, 0, -v196
	v_add_u32_e32 v51, -1, v52
	v_fma_f32 v53, -v51, v52, v50
	v_cmp_ge_f32_e64 s[42:43], 0, v53
	ds_bpermute_b32 v53, v235, v54
	v_add_u32_e32 v55, 1, v52
	v_cndmask_b32_e64 v51, v52, v51, s[42:43]
	v_fma_f32 v52, -v55, v52, v50
	v_cmp_lt_f32_e64 s[42:43], 0, v52
	s_waitcnt lgkmcnt(0)
	v_add_f32_e32 v52, v54, v53
	ds_bpermute_b32 v53, v236, v52
	v_cndmask_b32_e64 v51, v51, v55, s[42:43]
	v_mul_f32_e32 v54, 0x37800000, v51
	v_cndmask_b32_e32 v51, v51, v54, vcc
	v_cmp_class_f32_e32 vcc, v50, v216
	v_mov_b64_e32 v[72:73], v[80:81]
	v_mov_b64_e32 v[68:69], v[80:81]
	v_cndmask_b32_e32 v50, v51, v50, vcc
	s_waitcnt lgkmcnt(0)
	v_add_f32_e32 v51, v52, v53
	v_mul_f32_e32 v52, 0x4f800000, v51
	v_cmp_gt_f32_e32 vcc, s3, v51
	v_mul_f32_e64 v198, v48, -v50
	s_and_b32 s3, s6, 7
	v_cndmask_b32_e32 v51, v51, v52, vcc
	v_sqrt_f32_e32 v52, v51
	v_mov_b64_e32 v[64:65], v[80:81]
	v_mov_b64_e32 v[60:61], v[80:81]
	v_mov_b64_e32 v[56:57], v[80:81]
	v_add_u32_e32 v50, -1, v52
	v_fma_f32 v53, -v50, v52, v51
	v_cmp_ge_f32_e64 s[42:43], 0, v53
	v_add_u32_e32 v53, 1, v52
	v_mov_b32_e32 v193, v192
	v_cndmask_b32_e64 v50, v52, v50, s[42:43]
	v_fma_f32 v52, -v53, v52, v51
	v_cmp_lt_f32_e64 s[42:43], 0, v52
	v_mov_b32_e32 v197, v196
	v_mov_b32_e32 v199, v198
	v_cndmask_b32_e64 v50, v50, v53, s[42:43]
	v_mul_f32_e32 v52, 0x37800000, v50
	v_cndmask_b32_e32 v50, v50, v52, vcc
	v_cmp_class_f32_e32 vcc, v51, v216
	v_mov_b64_e32 v[52:53], v[80:81]
	s_mov_b32 s16, 0
	v_cndmask_b32_e32 v50, v50, v51, vcc
	v_mul_f32_e64 v200, v48, -v50
	v_max3_f32 v48, v49, -v198, -v200
	v_cmp_lt_f32_e32 vcc, s4, v48
	s_cmp_lg_u64 vcc, 0
	s_cselect_b64 s[4:5], -1, 0
	s_add_u32 s8, s44, s8
	s_addc_u32 s7, s45, s7
	s_lshl_b32 s9, s3, 8
	s_add_u32 s8, s8, s9
	s_addc_u32 s7, s7, 0
	s_add_u32 s8, s8, 0xe610080
	s_addc_u32 s9, s7, 0
	v_mov_b32_e32 v48, 0x18c000
	v_lshl_add_u64 v[204:205], s[8:9], 0, v[182:183]
	v_mad_i64_i32 v[202:203], s[6:7], s6, v48, v[188:189]
	v_lshl_add_u64 v[48:49], v[204:205], 0, v[166:167]
	global_load_dwordx4 v[112:115], v[202:203], off offset:16
	global_load_dwordx4 v[116:119], v[202:203], off
	global_load_dwordx4 v[120:123], v[202:203], off offset:32
	global_load_dwordx4 v[124:127], v[48:49], off
	v_lshl_add_u64 v[48:49], s[8:9], 0, v[184:185]
	v_lshl_add_u64 v[48:49], v[48:49], 0, v[166:167]
	global_load_dwordx4 v[128:131], v[48:49], off
	v_mov_b64_e32 v[48:49], v[80:81]
	v_mov_b32_e32 v201, v200
	s_mov_b64 s[6:7], 0
	v_mov_b64_e32 v[84:85], v[80:81]
	v_mov_b64_e32 v[88:89], v[80:81]
	v_mov_b64_e32 v[92:93], v[80:81]
	v_mov_b64_e32 v[96:97], v[80:81]
	v_mov_b64_e32 v[100:101], v[80:81]
	v_mov_b64_e32 v[104:105], v[80:81]
	v_mov_b64_e32 v[108:109], v[80:81]
	v_mov_b64_e32 v[78:79], v[82:83]
	v_mov_b64_e32 v[74:75], v[82:83]
	v_mov_b64_e32 v[70:71], v[82:83]
	v_mov_b64_e32 v[66:67], v[82:83]
	v_mov_b64_e32 v[62:63], v[82:83]
	v_mov_b64_e32 v[58:59], v[82:83]
	v_mov_b64_e32 v[54:55], v[82:83]
	v_mov_b64_e32 v[50:51], v[82:83]
	v_mov_b64_e32 v[194:195], v[190:191]
	v_lshrrev_b32_e32 v132, 4, v164
	v_lshrrev_b32_e32 v133, 5, v164
	v_xor_b32_e32 v132, v132, v133
	v_and_b32_e32 v132, 1, v132
	v_and_b32_e32 v133, 1, v164
	v_lshlrev_b32_e32 v133, 1, v133
	v_sub_u32_e32 v133, 1, v133
	v_mul_i32_i24_e32 v132, v132, v133
	v_lshlrev_b32_e32 v132, 4, v132
	v_add_u32_e32 v133, v237, v132
	v_sub_u32_e32 v134, v237, v132
	s_waitcnt vmcnt(3)
	ds_write_b128 v133, v[116:119]
	ds_write_b128 v134, v[112:115] offset:16
	s_waitcnt vmcnt(2)
	ds_write_b128 v133, v[120:123] offset:32
	s_waitcnt vmcnt(1)
	ds_write_b16 v238, v124 offset:53248
	ds_write_b16_d16_hi v238, v124 offset:53520
	ds_write_b16 v238, v125 offset:53792
	ds_write_b16_d16_hi v238, v125 offset:54064
	ds_write_b16 v238, v126 offset:54336
	ds_write_b16_d16_hi v238, v126 offset:54608
	ds_write_b16 v238, v127 offset:54880
	ds_write_b16_d16_hi v238, v127 offset:55152
	s_waitcnt vmcnt(0)
	ds_write_b16 v238, v128 offset:53376
	ds_write_b16_d16_hi v238, v128 offset:53648
	ds_write_b16 v238, v129 offset:53920
	ds_write_b16_d16_hi v238, v129 offset:54192
	ds_write_b16 v238, v130 offset:54464
	ds_write_b16_d16_hi v238, v130 offset:54736
	ds_write_b16 v238, v131 offset:55008
	ds_write_b16_d16_hi v238, v131 offset:55280
	s_waitcnt lgkmcnt(0)
	s_barrier

; __device__ __forceinline__ void attn_phase(const Params& p, char* smem) {
;     ...
;       if (kt + 1 < nkt) {
;         bf16_t* dK = Ks + (buf ^ 1) * KT * KLD;
;         bf16_t* dV = Vt + (buf ^ 1) * 64 * VLD;
;         *(uint4*)(dK + klo) = rk0; *(uint4*)(dK + klo + 8) = rk1; *(uint4*)(dK + klo + 16) = rk2;
;         vt_scatter(dV + (vch * 8) * VLD + vkey0, VLD, rv0); vt_scatter(dV + (vch * 8) * VLD + vkey0 + 64, VLD, rv1);
;       }
.LBB0_420:
	s_or_b64 exec, exec, s[10:11]
	s_andn2_b64 vcc, exec, s[8:9]
	s_cbranch_vccnz .LBB0_422
	s_andn2_b32 s8, 1, s16
	s_mul_i32 s9, s8, 0x6800
	s_mulk_i32 s8, 0x4400
	v_lshrrev_b32_e32 v133, 4, v164
	v_lshrrev_b32_e32 v134, 5, v164
	v_xor_b32_e32 v133, v133, v134
	v_and_b32_e32 v133, 1, v133
	v_and_b32_e32 v134, 1, v164
	v_lshlrev_b32_e32 v134, 1, v134
	v_sub_u32_e32 v134, 1, v134
	v_mul_i32_i24_e32 v133, v133, v134
	v_lshlrev_b32_e32 v133, 4, v133
	v_add_u32_e32 v132, s9, v237
	v_add_u32_e32 v135, v132, v133
	v_sub_u32_e32 v134, v132, v133
	s_waitcnt vmcnt(3)
	ds_write_b128 v135, v[116:119]
	ds_write_b128 v134, v[112:115] offset:16
	s_waitcnt vmcnt(2)
	ds_write_b128 v135, v[120:123] offset:32
	v_add_u32_e32 v132, s8, v238
	s_waitcnt vmcnt(1)
	ds_write_b16 v132, v124 offset:53248
	ds_write_b16_d16_hi v132, v124 offset:53520
	ds_write_b16 v132, v125 offset:53792
	ds_write_b16_d16_hi v132, v125 offset:54064
	ds_write_b16 v132, v126 offset:54336
	ds_write_b16_d16_hi v132, v126 offset:54608
	ds_write_b16 v132, v127 offset:54880
	ds_write_b16_d16_hi v132, v127 offset:55152
	s_waitcnt vmcnt(0)
	ds_write_b16 v132, v128 offset:53376
	ds_write_b16_d16_hi v132, v128 offset:53648
	ds_write_b16 v132, v129 offset:53920
	ds_write_b16_d16_hi v132, v129 offset:54192
	ds_write_b16 v132, v130 offset:54464
	ds_write_b16_d16_hi v132, v130 offset:54736
	ds_write_b16 v132, v131 offset:55008
	ds_write_b16_d16_hi v132, v131 offset:55280
